# static s_setprio 1 for waves 0-3 (mirror) during the attention phase
# baseline (speedup 1.0000x reference)
.LBB0_178:
	s_or_b64 exec, exec, s[6:7]
	s_waitcnt lgkmcnt(0)
	s_barrier
	v_mbcnt_lo_u32_b32 v2, -1, 0
	v_mbcnt_hi_u32_b32 v2, -1, v2
	s_load_dwordx2 s[6:7], s[0:1], 0x98
	s_waitcnt lgkmcnt(0)
	s_load_dwordx2 s[8:9], s[0:1], 16
	s_waitcnt lgkmcnt(0)
	s_load_dwordx2 s[10:11], s[0:1], 24
	s_waitcnt lgkmcnt(0)
	s_load_dwordx2 s[12:13], s[0:1], 32
	s_waitcnt lgkmcnt(0)
	s_load_dwordx2 s[14:15], s[0:1], 40
	s_waitcnt lgkmcnt(0)
	s_nop 0
	v_ashrrev_i32_e32 v3, 31, v2
	v_lshlrev_b64 v[4:5], 2, v[2:3]
	v_lshl_add_u64 v[6:7], s[8:9], 0, v[4:5]
	v_lshl_add_u64 v[8:9], s[10:11], 0, v[4:5]
	global_load_dword v10, v[6:7], off
	global_load_dword v11, v[6:7], off offset:256
	global_load_dword v12, v[8:9], off
	global_load_dword v13, v[8:9], off offset:256
	v_lshl_add_u64 v[6:7], s[12:13], 0, v[4:5]
	v_lshl_add_u64 v[4:5], s[14:15], 0, v[4:5]
	global_load_dword v8, v[6:7], off
	global_load_dword v9, v[6:7], off offset:256
	global_load_dword v14, v[4:5], off
	global_load_dword v15, v[4:5], off offset:256
	s_abs_i32 s13, s24
	v_cvt_f32_u32_e32 v3, s13
	v_lshlrev_b32_e32 v2, 2, v2
	v_xor_b32_e32 v6, 4, v2
	v_xor_b32_e32 v7, 8, v2
	v_xor_b32_e32 v16, 16, v2
	v_xor_b32_e32 v17, 32, v2
	v_xor_b32_e32 v18, 64, v2
	v_xor_b32_e32 v19, 0x80, v2
	v_rcp_iflag_f32_e32 v20, v3
	v_readfirstlane_b32 s10, v0
	s_lshr_b32 s10, s10, 4
	s_and_b32 s10, s10, 0xffffffc
	s_add_i32 s10, s10, 0
	s_mov_b32 s8, 0x3fb8aa3b
	s_add_i32 s29, s10, 0x20c00
	s_sub_i32 s15, 0, s13
	s_sub_i32 s11, s24, s17
	s_add_i32 s14, s11, 0x1ff
	s_sub_i32 s11, 0xfffffe01, s11
	s_xor_b32 s28, s14, s24
	s_max_i32 s14, s14, s11
	s_mov_b32 s9, 0xc2ce8ed0
	s_mov_b32 s12, 0x42b17218
	v_mov_b32_e32 v1, 0x7f800000
	s_ashr_i32 s28, s28, 31
	s_load_dwordx2 s[10:11], s[0:1], 48
	s_waitcnt lgkmcnt(0)
	s_mov_b32 s25, 0
	s_waitcnt vmcnt(4)
	v_pk_mul_f32 v[2:3], v[10:11], v[12:13]
	s_nop 0
	v_add_f32_e32 v2, v2, v3
	s_waitcnt vmcnt(0)
	v_pk_mul_f32 v[4:5], v[8:9], v[14:15]
	s_nop 0
	v_add_f32_e32 v3, v4, v5
	ds_bpermute_b32 v4, v6, v2
	ds_bpermute_b32 v5, v6, v3
	v_mul_f32_e32 v8, 0x4f7ffffe, v20
	v_cvt_u32_f32_e32 v8, v8
	v_mov_b32_e32 v6, s29
	s_waitcnt lgkmcnt(1)
	v_add_f32_e32 v2, v2, v4
	s_waitcnt lgkmcnt(0)
	v_add_f32_e32 v3, v3, v5
	ds_bpermute_b32 v4, v7, v2
	ds_bpermute_b32 v5, v7, v3
	v_readfirstlane_b32 s29, v8
	s_mul_i32 s15, s15, s29
	s_mul_hi_u32 s15, s29, s15
	s_waitcnt lgkmcnt(1)
	v_add_f32_e32 v2, v2, v4
	s_waitcnt lgkmcnt(0)
	v_add_f32_e32 v3, v3, v5
	ds_bpermute_b32 v4, v16, v2
	ds_bpermute_b32 v5, v16, v3
	s_add_i32 s29, s29, s15
	s_mul_hi_u32 s15, s14, s29
	s_mul_i32 s29, s15, s13
	s_waitcnt lgkmcnt(1)
	v_add_f32_e32 v2, v2, v4
	s_waitcnt lgkmcnt(0)
	v_add_f32_e32 v3, v3, v5
	ds_bpermute_b32 v4, v17, v2
	ds_bpermute_b32 v5, v17, v3
	s_sub_i32 s14, s14, s29
	s_add_i32 s30, s15, 1
	s_sub_i32 s29, s14, s13
	s_waitcnt lgkmcnt(1)
	v_add_f32_e32 v2, v2, v4
	s_waitcnt lgkmcnt(0)
	v_add_f32_e32 v3, v3, v5
	ds_bpermute_b32 v4, v18, v2
	ds_bpermute_b32 v5, v18, v3
	s_cmp_ge_u32 s14, s13
	s_cselect_b32 s15, s30, s15
	s_cselect_b32 s14, s29, s14
	s_waitcnt lgkmcnt(1)
	v_add_f32_e32 v2, v2, v4
	s_waitcnt lgkmcnt(0)
	v_add_f32_e32 v3, v3, v5
	ds_bpermute_b32 v4, v19, v2
	ds_bpermute_b32 v5, v19, v3
	s_add_i32 s29, s15, 1
	s_cmp_ge_u32 s14, s13
	s_cselect_b32 s13, s29, s15
	s_waitcnt lgkmcnt(1)
	v_add_f32_e32 v2, v2, v4
	s_waitcnt lgkmcnt(0)
	v_add_f32_e32 v3, v3, v5
	v_mul_f32_e32 v4, 0x3fb8aa3b, v2
	v_mul_f32_e32 v5, 0x3fb8aa3b, v3
	v_fma_f32 v7, v2, s8, -v4
	v_rndne_f32_e32 v8, v4
	v_fma_f32 v9, v3, s8, -v5
	v_rndne_f32_e32 v10, v5
	v_fmac_f32_e32 v7, 0x32a5705f, v2
	v_sub_f32_e32 v4, v4, v8
	v_fmac_f32_e32 v9, 0x32a5705f, v3
	v_sub_f32_e32 v5, v5, v10
	v_add_f32_e32 v4, v4, v7
	v_cvt_i32_f32_e32 v8, v8
	v_add_f32_e32 v5, v5, v9
	v_exp_f32_e32 v4, v4
	v_cvt_i32_f32_e32 v10, v10
	v_exp_f32_e32 v5, v5
	v_cmp_ngt_f32_e32 vcc, s9, v2
	v_ldexp_f32 v4, v4, v8
	s_xor_b32 s8, s13, s28
	v_ldexp_f32 v5, v5, v10
	v_cndmask_b32_e32 v4, 0, v4, vcc
	v_cmp_ngt_f32_e32 vcc, s9, v3
	s_sub_i32 s8, s8, s28
	s_cmp_lt_i32 s8, 1
	v_cndmask_b32_e32 v5, 0, v5, vcc
	v_cmp_nlt_f32_e32 vcc, s12, v2
	s_nop 1
	v_cndmask_b32_e32 v2, v1, v4, vcc
	v_cmp_nlt_f32_e32 vcc, s12, v3
	s_nop 1
	v_cndmask_b32_e32 v1, v1, v5, vcc
	v_sub_f32_e32 v1, v2, v1
	v_add_f32_e32 v1, 0x3e4ccccd, v1
	ds_write_b32 v6, v1
	s_waitcnt lgkmcnt(0)
	s_cbranch_scc1 .LBB0_463
	s_add_u32 s38, s6, 0x16100000
	s_addc_u32 s39, s7, 0
	s_add_u32 s40, s6, 0x3e100000
	s_addc_u32 s41, s7, 0
	s_lshl_b32 s8, s8, 1
	s_max_i32 s42, s8, 1
	s_add_u32 s43, s6, 0x16601100
	s_mov_b32 s14, 0xffd7ff00
	s_mov_b32 s28, 0xffd80000
	s_movk_i32 s30, 0xff00
	s_addc_u32 s44, s7, 0
	s_movk_i32 s45, 0x5000
	s_mov_b64 s[12:13], 0x100
	v_mov_b32_e32 v223, 0
	s_brev_b32 s46, -2
	s_add_i32 s47, 0, 0x18000
	s_mov_b32 s15, -1
	s_mov_b32 s29, -1
	s_movk_i32 s48, 0x70
	s_brev_b32 s49, 1
	s_mov_b32 s50, 0x41000000
	s_movk_i32 s51, 0x100
	s_mov_b32 s31, -1
	s_movk_i32 s52, 0xc000
	v_mov_b32_e32 v1, 0x3727c5ac
	s_mov_b32 s53, 0xf800000
	v_mov_b32_e32 v224, 0x260
	v_mov_b32_e32 v225, 0xff800000
	v_mbcnt_lo_u32_b32 v255, -1, 0
	v_mbcnt_hi_u32_b32 v255, -1, v255
	v_lshrrev_b32_e32 v251, 4, v255
	v_and_b32_e32 v252, 15, v255
	v_xor_b32_e32 v252, v252, v251
	v_lshlrev_b32_e32 v252, 4, v252
	v_mul_u32_u24_e32 v251, 0xa000, v251
	v_add_u32_e32 v251, v251, v252
	s_mul_i32 s98, s19, 0x50000
	v_add_u32_e32 v251, s98, v251
	v_xor_b32_e32 v252, 64, v251
	v_add_u32_e32 v252, 0x28000, v252
	v_bfe_u32 v253, v255, 2, 3
	s_and_b32 s98, s19, 1
	s_lshl_b32 s98, s98, 4
	v_or_b32_e32 v253, s98, v253
	v_mul_u32_u24_e32 v253, 0xa000, v253
	v_lshrrev_b32_e32 v254, 5, v255
	v_lshlrev_b32_e32 v254, 6, v254
	v_add_u32_e32 v253, v253, v254
	v_bfe_u32 v254, v255, 4, 1
	v_xor_b32_e32 v254, v254, v255
	v_and_b32_e32 v254, 3, v254
	v_lshlrev_b32_e32 v254, 4, v254
	v_add_u32_e32 v253, v253, v254
	v_xor_b32_e32 v254, 32, v253
	v_add_u32_e32 v254, 0x50000, v254
	v_lshrrev_b32_e32 v2, 3, v255
	v_ashrrev_i32_e32 v3, 5, v255
	v_and_or_b32 v2, v2, 2, v3
	v_lshlrev_b32_e32 v3, 1, v3
	v_bfe_u32 v5, v255, 1, 1
	v_and_b32_e32 v3, 2, v3
	v_and_b32_e32 v6, 12, v255
	v_or3_b32 v5, v6, v3, v5
	v_lshlrev_b32_e32 v2, 11, v2
	v_lshlrev_b32_e32 v7, 3, v255
	v_and_b32_e32 v7, 8, v7
	v_lshlrev_b32_e32 v5, 4, v5
	v_add3_u32 v255, v7, v2, v5
	s_cmp_ge_u32 s19, 4
	s_cbranch_scc1 .Lattn_prio_skip
	s_setprio 1
